# UP epilogue: per-block store address from one 64-bit base plus scalar row offset (drops 64-bit multiply-adds)
# baseline (speedup 1.0000x reference)
.LBB0_652:
	v_lshl_add_u32 v142, v151, 2, s44
	ds_read2_b32 v[148:149], v142 offset1:16
	ds_read2_b32 v[146:147], v142 offset0:32 offset1:48
	ds_read2_b32 v[144:145], v142 offset0:64 offset1:80
	ds_read2_b32 v[142:143], v142 offset0:96 offset1:112
	v_add_u32_e32 v155, s4, v151
	s_waitcnt lgkmcnt(0)
	v_pk_mul_f32 v[126:127], v[126:127], v[148:149] op_sel_hi:[1,0]
	v_pk_mul_f32 v[122:123], v[122:123], v[148:149] op_sel_hi:[1,0]
	v_pk_mul_f32 v[118:119], v[118:119], v[148:149] op_sel_hi:[1,0]
	v_pk_mul_f32 v[114:115], v[114:115], v[148:149] op_sel_hi:[1,0]
	v_pk_mul_f32 v[128:129], v[128:129], v[148:149] op_sel_hi:[1,0]
	v_pk_mul_f32 v[124:125], v[124:125], v[148:149] op_sel_hi:[1,0]
	v_pk_mul_f32 v[120:121], v[120:121], v[148:149] op_sel_hi:[1,0]
	v_pk_mul_f32 v[116:117], v[116:117], v[148:149] op_sel_hi:[1,0]
	v_mov_b32_e32 v176, 0xbfb8aa3b
	v_pk_mul_f32 v[168:169], v[126:127], v[176:177] op_sel_hi:[1,0]
	v_pk_mul_f32 v[170:171], v[122:123], v[176:177] op_sel_hi:[1,0]
	v_pk_mul_f32 v[172:173], v[128:129], v[176:177] op_sel_hi:[1,0]
	v_pk_mul_f32 v[174:175], v[124:125], v[176:177] op_sel_hi:[1,0]
	v_exp_f32_e32 v168, v168
	v_exp_f32_e32 v169, v169
	v_exp_f32_e32 v170, v170
	v_exp_f32_e32 v171, v171
	v_exp_f32_e32 v172, v172
	v_exp_f32_e32 v173, v173
	v_exp_f32_e32 v174, v174
	v_exp_f32_e32 v175, v175
	v_pk_add_f32 v[168:169], v[168:169], 1.0 op_sel_hi:[1,0]
	v_pk_add_f32 v[170:171], v[170:171], 1.0 op_sel_hi:[1,0]
	v_pk_add_f32 v[172:173], v[172:173], 1.0 op_sel_hi:[1,0]
	v_pk_add_f32 v[174:175], v[174:175], 1.0 op_sel_hi:[1,0]
	v_rcp_f32_e32 v168, v168
	v_rcp_f32_e32 v169, v169
	v_rcp_f32_e32 v170, v170
	v_rcp_f32_e32 v171, v171
	v_rcp_f32_e32 v172, v172
	v_rcp_f32_e32 v173, v173
	v_rcp_f32_e32 v174, v174
	v_rcp_f32_e32 v175, v175
	v_pk_mul_f32 v[168:169], v[126:127], v[168:169]
	v_pk_mul_f32 v[170:171], v[122:123], v[170:171]
	v_pk_mul_f32 v[172:173], v[128:129], v[172:173]
	v_pk_mul_f32 v[174:175], v[124:125], v[174:175]
	v_pk_mul_f32 v[118:119], v[118:119], v[168:169]
	v_pk_mul_f32 v[114:115], v[114:115], v[170:171]
	v_pk_mul_f32 v[120:121], v[120:121], v[172:173]
	v_pk_mul_f32 v[116:117], v[116:117], v[174:175]
	s_lshl_b32 s0, s47, 7
	s_ashr_i32 s1, s0, 31
	v_add_u32_e32 v148, s50, v155
	s_movk_i32 s18, 0x1600
	v_lshlrev_b32_e32 v150, 3, v150
	s_lshl_b64 s[0:1], s[0:1], 1
	v_ashrrev_i32_e32 v151, 31, v150
	v_pk_mul_f32 v[94:95], v[94:95], v[146:147] op_sel_hi:[1,0]
	v_pk_mul_f32 v[90:91], v[90:91], v[146:147] op_sel_hi:[1,0]
	v_pk_mul_f32 v[86:87], v[86:87], v[146:147] op_sel_hi:[1,0]
	v_pk_mul_f32 v[82:83], v[82:83], v[146:147] op_sel_hi:[1,0]
	v_pk_mul_f32 v[96:97], v[96:97], v[146:147] op_sel_hi:[1,0]
	v_cvt_pk_bf16_f32 v118, v118, v119
	v_pk_mul_f32 v[92:93], v[92:93], v[146:147] op_sel_hi:[1,0]
	v_pk_mul_f32 v[88:89], v[88:89], v[146:147] op_sel_hi:[1,0]
	v_pk_mul_f32 v[84:85], v[84:85], v[146:147] op_sel_hi:[1,0]
	v_pk_mul_f32 v[62:63], v[62:63], v[144:145] op_sel_hi:[1,0]
	v_pk_mul_f32 v[58:59], v[58:59], v[144:145] op_sel_hi:[1,0]
	v_pk_mul_f32 v[54:55], v[54:55], v[144:145] op_sel_hi:[1,0]
	v_pk_mul_f32 v[50:51], v[50:51], v[144:145] op_sel_hi:[1,0]
	v_pk_mul_f32 v[64:65], v[64:65], v[144:145] op_sel_hi:[1,0]
	v_pk_mul_f32 v[60:61], v[60:61], v[144:145] op_sel_hi:[1,0]
	v_pk_mul_f32 v[56:57], v[56:57], v[144:145] op_sel_hi:[1,0]
	v_pk_mul_f32 v[52:53], v[52:53], v[144:145] op_sel_hi:[1,0]
	v_pk_mul_f32 v[30:31], v[30:31], v[142:143] op_sel_hi:[1,0]
	v_pk_mul_f32 v[26:27], v[26:27], v[142:143] op_sel_hi:[1,0]
	v_pk_mul_f32 v[22:23], v[22:23], v[142:143] op_sel_hi:[1,0]
	v_pk_mul_f32 v[18:19], v[18:19], v[142:143] op_sel_hi:[1,0]
	v_pk_mul_f32 v[32:33], v[32:33], v[142:143] op_sel_hi:[1,0]
	v_pk_mul_f32 v[28:29], v[28:29], v[142:143] op_sel_hi:[1,0]
	v_pk_mul_f32 v[24:25], v[24:25], v[142:143] op_sel_hi:[1,0]
	v_pk_mul_f32 v[20:21], v[20:21], v[142:143] op_sel_hi:[1,0]
	s_and_b64 vcc, exec, s[8:9]
	s_mov_b32 s47, s46
	s_mov_b32 s48, s45
	v_cvt_pk_bf16_f32 v119, v120, v121
	v_cvt_pk_bf16_f32 v120, v114, v115
	v_mov_b64_e32 v[114:115], s[2:3]
	v_cvt_pk_bf16_f32 v121, v116, v117
	v_mad_i64_i32 v[116:117], s[4:5], v148, s18, v[114:115]
	v_lshl_add_u64 v[116:117], v[116:117], 0, s[0:1]
	v_lshl_add_u64 v[122:123], v[116:117], 0, s[92:93]
	v_lshlrev_b64 v[116:117], 1, v[150:151]
	v_lshl_add_u64 v[122:123], v[122:123], 0, v[116:117]
	v_mov_b64_e32 v[246:247], v[122:123]
	global_store_dwordx4 v[122:123], v[118:121], off nt
	s_nop 1
	v_mov_b32_e32 v118, v149
	v_pk_mul_f32 v[110:111], v[110:111], v[118:119] op_sel_hi:[1,0]
	v_pk_mul_f32 v[112:113], v[112:113], v[118:119] op_sel_hi:[1,0]
	v_pk_mul_f32 v[108:109], v[108:109], v[118:119] op_sel_hi:[1,0]
	v_pk_mul_f32 v[106:107], v[106:107], v[118:119] op_sel_hi:[1,0]
	v_pk_mul_f32 v[104:105], v[104:105], v[118:119] op_sel_hi:[1,0]
	v_pk_mul_f32 v[102:103], v[102:103], v[118:119] op_sel_hi:[1,0]
	v_pk_mul_f32 v[100:101], v[100:101], v[118:119] op_sel_hi:[1,0]
	v_pk_mul_f32 v[98:99], v[98:99], v[118:119] op_sel_hi:[1,0]
	v_pk_mul_f32 v[168:169], v[110:111], v[176:177] op_sel_hi:[1,0]
	v_pk_mul_f32 v[170:171], v[106:107], v[176:177] op_sel_hi:[1,0]
	v_pk_mul_f32 v[172:173], v[112:113], v[176:177] op_sel_hi:[1,0]
	v_pk_mul_f32 v[174:175], v[108:109], v[176:177] op_sel_hi:[1,0]
	v_exp_f32_e32 v168, v168
	v_exp_f32_e32 v169, v169
	v_exp_f32_e32 v170, v170
	v_exp_f32_e32 v171, v171
	v_exp_f32_e32 v172, v172
	v_exp_f32_e32 v173, v173
	v_exp_f32_e32 v174, v174
	v_exp_f32_e32 v175, v175
	v_pk_add_f32 v[168:169], v[168:169], 1.0 op_sel_hi:[1,0]
	v_pk_add_f32 v[170:171], v[170:171], 1.0 op_sel_hi:[1,0]
	v_pk_add_f32 v[172:173], v[172:173], 1.0 op_sel_hi:[1,0]
	v_pk_add_f32 v[174:175], v[174:175], 1.0 op_sel_hi:[1,0]
	v_rcp_f32_e32 v168, v168
	v_rcp_f32_e32 v169, v169
	v_rcp_f32_e32 v170, v170
	v_rcp_f32_e32 v171, v171
	v_rcp_f32_e32 v172, v172
	v_rcp_f32_e32 v173, v173
	v_rcp_f32_e32 v174, v174
	v_rcp_f32_e32 v175, v175
	v_pk_mul_f32 v[168:169], v[110:111], v[168:169]
	v_pk_mul_f32 v[170:171], v[106:107], v[170:171]
	v_pk_mul_f32 v[172:173], v[112:113], v[172:173]
	v_pk_mul_f32 v[174:175], v[108:109], v[174:175]
	v_pk_mul_f32 v[110:111], v[102:103], v[168:169]
	v_pk_mul_f32 v[106:107], v[98:99], v[170:171]
	v_pk_mul_f32 v[112:113], v[104:105], v[172:173]
	v_pk_mul_f32 v[108:109], v[100:101], v[174:175]
	v_cvt_pk_bf16_f32 v98, v110, v111
	v_cvt_pk_bf16_f32 v99, v112, v113
	v_cvt_pk_bf16_f32 v100, v106, v107
	s_sub_i32 s96, s83, s50
	s_mul_i32 s96, s96, 0x1600
	s_ashr_i32 s97, s96, 31
	v_lshl_add_u64 v[102:103], v[246:247], 0, s[96:97]
	v_cvt_pk_bf16_f32 v101, v108, v109
	global_store_dwordx4 v[102:103], v[98:101], off nt
	s_nop 1
	v_pk_mul_f32 v[168:169], v[94:95], v[176:177] op_sel_hi:[1,0]
	v_pk_mul_f32 v[170:171], v[90:91], v[176:177] op_sel_hi:[1,0]
	v_pk_mul_f32 v[172:173], v[96:97], v[176:177] op_sel_hi:[1,0]
	v_pk_mul_f32 v[174:175], v[92:93], v[176:177] op_sel_hi:[1,0]
	v_exp_f32_e32 v168, v168
	v_exp_f32_e32 v169, v169
	v_exp_f32_e32 v170, v170
	v_exp_f32_e32 v171, v171
	v_exp_f32_e32 v172, v172
	v_exp_f32_e32 v173, v173
	v_exp_f32_e32 v174, v174
	v_exp_f32_e32 v175, v175
	v_pk_add_f32 v[168:169], v[168:169], 1.0 op_sel_hi:[1,0]
	v_pk_add_f32 v[170:171], v[170:171], 1.0 op_sel_hi:[1,0]
	v_pk_add_f32 v[172:173], v[172:173], 1.0 op_sel_hi:[1,0]
	v_pk_add_f32 v[174:175], v[174:175], 1.0 op_sel_hi:[1,0]
	v_rcp_f32_e32 v168, v168
	v_rcp_f32_e32 v169, v169
	v_rcp_f32_e32 v170, v170
	v_rcp_f32_e32 v171, v171
	v_rcp_f32_e32 v172, v172
	v_rcp_f32_e32 v173, v173
	v_rcp_f32_e32 v174, v174
	v_rcp_f32_e32 v175, v175
	v_pk_mul_f32 v[168:169], v[94:95], v[168:169]
	v_pk_mul_f32 v[170:171], v[90:91], v[170:171]
	v_pk_mul_f32 v[172:173], v[96:97], v[172:173]
	v_pk_mul_f32 v[174:175], v[92:93], v[174:175]
	v_pk_mul_f32 v[94:95], v[86:87], v[168:169]
	v_pk_mul_f32 v[90:91], v[82:83], v[170:171]
	v_pk_mul_f32 v[96:97], v[88:89], v[172:173]
	v_pk_mul_f32 v[92:93], v[84:85], v[174:175]
	v_cvt_pk_bf16_f32 v82, v94, v95
	v_cvt_pk_bf16_f32 v83, v96, v97
	v_cvt_pk_bf16_f32 v84, v90, v91
	s_sub_i32 s96, s91, s50
	s_mul_i32 s96, s96, 0x1600
	s_ashr_i32 s97, s96, 31
	v_lshl_add_u64 v[86:87], v[246:247], 0, s[96:97]
	v_cvt_pk_bf16_f32 v85, v92, v93
	global_store_dwordx4 v[86:87], v[82:85], off nt
	s_nop 1
	v_mov_b32_e32 v82, v147
	v_pk_mul_f32 v[78:79], v[78:79], v[82:83] op_sel_hi:[1,0]
	v_pk_mul_f32 v[80:81], v[80:81], v[82:83] op_sel_hi:[1,0]
	v_pk_mul_f32 v[76:77], v[76:77], v[82:83] op_sel_hi:[1,0]
	v_pk_mul_f32 v[74:75], v[74:75], v[82:83] op_sel_hi:[1,0]
	v_pk_mul_f32 v[72:73], v[72:73], v[82:83] op_sel_hi:[1,0]
	v_pk_mul_f32 v[70:71], v[70:71], v[82:83] op_sel_hi:[1,0]
	v_pk_mul_f32 v[68:69], v[68:69], v[82:83] op_sel_hi:[1,0]
	v_pk_mul_f32 v[66:67], v[66:67], v[82:83] op_sel_hi:[1,0]
	v_pk_mul_f32 v[168:169], v[78:79], v[176:177] op_sel_hi:[1,0]
	v_pk_mul_f32 v[170:171], v[74:75], v[176:177] op_sel_hi:[1,0]
	v_pk_mul_f32 v[172:173], v[80:81], v[176:177] op_sel_hi:[1,0]
	v_pk_mul_f32 v[174:175], v[76:77], v[176:177] op_sel_hi:[1,0]
	v_exp_f32_e32 v168, v168
	v_exp_f32_e32 v169, v169
	v_exp_f32_e32 v170, v170
	v_exp_f32_e32 v171, v171
	v_exp_f32_e32 v172, v172
	v_exp_f32_e32 v173, v173
	v_exp_f32_e32 v174, v174
	v_exp_f32_e32 v175, v175
	v_pk_add_f32 v[168:169], v[168:169], 1.0 op_sel_hi:[1,0]
	v_pk_add_f32 v[170:171], v[170:171], 1.0 op_sel_hi:[1,0]
	v_pk_add_f32 v[172:173], v[172:173], 1.0 op_sel_hi:[1,0]
	v_pk_add_f32 v[174:175], v[174:175], 1.0 op_sel_hi:[1,0]
	v_rcp_f32_e32 v168, v168
	v_rcp_f32_e32 v169, v169
	v_rcp_f32_e32 v170, v170
	v_rcp_f32_e32 v171, v171
	v_rcp_f32_e32 v172, v172
	v_rcp_f32_e32 v173, v173
	v_rcp_f32_e32 v174, v174
	v_rcp_f32_e32 v175, v175
	v_pk_mul_f32 v[168:169], v[78:79], v[168:169]
	v_pk_mul_f32 v[170:171], v[74:75], v[170:171]
	v_pk_mul_f32 v[172:173], v[80:81], v[172:173]
	v_pk_mul_f32 v[174:175], v[76:77], v[174:175]
	v_pk_mul_f32 v[78:79], v[70:71], v[168:169]
	v_pk_mul_f32 v[74:75], v[66:67], v[170:171]
	v_pk_mul_f32 v[80:81], v[72:73], v[172:173]
	v_pk_mul_f32 v[76:77], v[68:69], v[174:175]
	v_cvt_pk_bf16_f32 v66, v78, v79
	v_cvt_pk_bf16_f32 v67, v80, v81
	v_cvt_pk_bf16_f32 v68, v74, v75
	s_sub_i32 s96, s51, s50
	s_mul_i32 s96, s96, 0x1600
	s_ashr_i32 s97, s96, 31
	v_lshl_add_u64 v[70:71], v[246:247], 0, s[96:97]
	v_cvt_pk_bf16_f32 v69, v76, v77
	global_store_dwordx4 v[70:71], v[66:69], off nt
	s_nop 1
	v_pk_mul_f32 v[168:169], v[62:63], v[176:177] op_sel_hi:[1,0]
	v_pk_mul_f32 v[170:171], v[58:59], v[176:177] op_sel_hi:[1,0]
	v_pk_mul_f32 v[172:173], v[64:65], v[176:177] op_sel_hi:[1,0]
	v_pk_mul_f32 v[174:175], v[60:61], v[176:177] op_sel_hi:[1,0]
	v_exp_f32_e32 v168, v168
	v_exp_f32_e32 v169, v169
	v_exp_f32_e32 v170, v170
	v_exp_f32_e32 v171, v171
	v_exp_f32_e32 v172, v172
	v_exp_f32_e32 v173, v173
	v_exp_f32_e32 v174, v174
	v_exp_f32_e32 v175, v175
	v_pk_add_f32 v[168:169], v[168:169], 1.0 op_sel_hi:[1,0]
	v_pk_add_f32 v[170:171], v[170:171], 1.0 op_sel_hi:[1,0]
	v_pk_add_f32 v[172:173], v[172:173], 1.0 op_sel_hi:[1,0]
	v_pk_add_f32 v[174:175], v[174:175], 1.0 op_sel_hi:[1,0]
	v_rcp_f32_e32 v168, v168
	v_rcp_f32_e32 v169, v169
	v_rcp_f32_e32 v170, v170
	v_rcp_f32_e32 v171, v171
	v_rcp_f32_e32 v172, v172
	v_rcp_f32_e32 v173, v173
	v_rcp_f32_e32 v174, v174
	v_rcp_f32_e32 v175, v175
	v_pk_mul_f32 v[168:169], v[62:63], v[168:169]
	v_pk_mul_f32 v[170:171], v[58:59], v[170:171]
	v_pk_mul_f32 v[172:173], v[64:65], v[172:173]
	v_pk_mul_f32 v[174:175], v[60:61], v[174:175]
	v_pk_mul_f32 v[62:63], v[54:55], v[168:169]
	v_pk_mul_f32 v[58:59], v[50:51], v[170:171]
	v_pk_mul_f32 v[64:65], v[56:57], v[172:173]
	v_pk_mul_f32 v[60:61], v[52:53], v[174:175]
	v_cvt_pk_bf16_f32 v50, v62, v63
	v_cvt_pk_bf16_f32 v51, v64, v65
	v_cvt_pk_bf16_f32 v52, v58, v59
	s_sub_i32 s96, s88, s50
	s_mul_i32 s96, s96, 0x1600
	s_ashr_i32 s97, s96, 31
	v_lshl_add_u64 v[54:55], v[246:247], 0, s[96:97]
	v_cvt_pk_bf16_f32 v53, v60, v61
	global_store_dwordx4 v[54:55], v[50:53], off nt
	s_nop 1
	v_mov_b32_e32 v50, v145
	v_pk_mul_f32 v[46:47], v[46:47], v[50:51] op_sel_hi:[1,0]
	v_pk_mul_f32 v[48:49], v[48:49], v[50:51] op_sel_hi:[1,0]
	v_pk_mul_f32 v[44:45], v[44:45], v[50:51] op_sel_hi:[1,0]
	v_pk_mul_f32 v[42:43], v[42:43], v[50:51] op_sel_hi:[1,0]
	v_pk_mul_f32 v[40:41], v[40:41], v[50:51] op_sel_hi:[1,0]
	v_pk_mul_f32 v[38:39], v[38:39], v[50:51] op_sel_hi:[1,0]
	v_pk_mul_f32 v[36:37], v[36:37], v[50:51] op_sel_hi:[1,0]
	v_pk_mul_f32 v[34:35], v[34:35], v[50:51] op_sel_hi:[1,0]
	v_pk_mul_f32 v[168:169], v[46:47], v[176:177] op_sel_hi:[1,0]
	v_pk_mul_f32 v[170:171], v[42:43], v[176:177] op_sel_hi:[1,0]
	v_pk_mul_f32 v[172:173], v[48:49], v[176:177] op_sel_hi:[1,0]
	v_pk_mul_f32 v[174:175], v[44:45], v[176:177] op_sel_hi:[1,0]
	v_exp_f32_e32 v168, v168
	v_exp_f32_e32 v169, v169
	v_exp_f32_e32 v170, v170
	v_exp_f32_e32 v171, v171
	v_exp_f32_e32 v172, v172
	v_exp_f32_e32 v173, v173
	v_exp_f32_e32 v174, v174
	v_exp_f32_e32 v175, v175
	v_pk_add_f32 v[168:169], v[168:169], 1.0 op_sel_hi:[1,0]
	v_pk_add_f32 v[170:171], v[170:171], 1.0 op_sel_hi:[1,0]
	v_pk_add_f32 v[172:173], v[172:173], 1.0 op_sel_hi:[1,0]
	v_pk_add_f32 v[174:175], v[174:175], 1.0 op_sel_hi:[1,0]
	v_rcp_f32_e32 v168, v168
	v_rcp_f32_e32 v169, v169
	v_rcp_f32_e32 v170, v170
	v_rcp_f32_e32 v171, v171
	v_rcp_f32_e32 v172, v172
	v_rcp_f32_e32 v173, v173
	v_rcp_f32_e32 v174, v174
	v_rcp_f32_e32 v175, v175
	v_pk_mul_f32 v[168:169], v[46:47], v[168:169]
	v_pk_mul_f32 v[170:171], v[42:43], v[170:171]
	v_pk_mul_f32 v[172:173], v[48:49], v[172:173]
	v_pk_mul_f32 v[174:175], v[44:45], v[174:175]
	v_pk_mul_f32 v[46:47], v[38:39], v[168:169]
	v_pk_mul_f32 v[42:43], v[34:35], v[170:171]
	v_pk_mul_f32 v[48:49], v[40:41], v[172:173]
	v_pk_mul_f32 v[44:45], v[36:37], v[174:175]
	v_cvt_pk_bf16_f32 v34, v46, v47
	v_cvt_pk_bf16_f32 v35, v48, v49
	v_cvt_pk_bf16_f32 v36, v42, v43
	s_sub_i32 s96, s60, s50
	s_mul_i32 s96, s96, 0x1600
	s_ashr_i32 s97, s96, 31
	v_lshl_add_u64 v[38:39], v[246:247], 0, s[96:97]
	v_cvt_pk_bf16_f32 v37, v44, v45
	global_store_dwordx4 v[38:39], v[34:37], off nt
	s_nop 1
	v_pk_mul_f32 v[168:169], v[30:31], v[176:177] op_sel_hi:[1,0]
	v_pk_mul_f32 v[170:171], v[26:27], v[176:177] op_sel_hi:[1,0]
	v_pk_mul_f32 v[172:173], v[32:33], v[176:177] op_sel_hi:[1,0]
	v_pk_mul_f32 v[174:175], v[28:29], v[176:177] op_sel_hi:[1,0]
	v_exp_f32_e32 v168, v168
	v_exp_f32_e32 v169, v169
	v_exp_f32_e32 v170, v170
	v_exp_f32_e32 v171, v171
	v_exp_f32_e32 v172, v172
	v_exp_f32_e32 v173, v173
	v_exp_f32_e32 v174, v174
	v_exp_f32_e32 v175, v175
	v_pk_add_f32 v[168:169], v[168:169], 1.0 op_sel_hi:[1,0]
	v_pk_add_f32 v[170:171], v[170:171], 1.0 op_sel_hi:[1,0]
	v_pk_add_f32 v[172:173], v[172:173], 1.0 op_sel_hi:[1,0]
	v_pk_add_f32 v[174:175], v[174:175], 1.0 op_sel_hi:[1,0]
	v_rcp_f32_e32 v168, v168
	v_rcp_f32_e32 v169, v169
	v_rcp_f32_e32 v170, v170
	v_rcp_f32_e32 v171, v171
	v_rcp_f32_e32 v172, v172
	v_rcp_f32_e32 v173, v173
	v_rcp_f32_e32 v174, v174
	v_rcp_f32_e32 v175, v175
	v_pk_mul_f32 v[168:169], v[30:31], v[168:169]
	v_pk_mul_f32 v[170:171], v[26:27], v[170:171]
	v_pk_mul_f32 v[172:173], v[32:33], v[172:173]
	v_pk_mul_f32 v[174:175], v[28:29], v[174:175]
	v_pk_mul_f32 v[30:31], v[22:23], v[168:169]
	v_pk_mul_f32 v[26:27], v[18:19], v[170:171]
	v_pk_mul_f32 v[32:33], v[24:25], v[172:173]
	v_pk_mul_f32 v[28:29], v[20:21], v[174:175]
	v_cvt_pk_bf16_f32 v18, v30, v31
	v_cvt_pk_bf16_f32 v19, v32, v33
	v_cvt_pk_bf16_f32 v20, v26, v27
	s_sub_i32 s96, s61, s50
	s_mul_i32 s96, s96, 0x1600
	s_ashr_i32 s97, s96, 31
	v_lshl_add_u64 v[22:23], v[246:247], 0, s[96:97]
	v_cvt_pk_bf16_f32 v21, v28, v29
	global_store_dwordx4 v[22:23], v[18:21], off nt
	s_nop 1
	v_mov_b32_e32 v18, v143
	v_pk_mul_f32 v[14:15], v[14:15], v[18:19] op_sel_hi:[1,0]
	v_pk_mul_f32 v[16:17], v[16:17], v[18:19] op_sel_hi:[1,0]
	v_pk_mul_f32 v[12:13], v[12:13], v[18:19] op_sel_hi:[1,0]
	v_pk_mul_f32 v[10:11], v[10:11], v[18:19] op_sel_hi:[1,0]
	v_pk_mul_f32 v[8:9], v[8:9], v[18:19] op_sel_hi:[1,0]
	v_pk_mul_f32 v[6:7], v[6:7], v[18:19] op_sel_hi:[1,0]
	v_pk_mul_f32 v[4:5], v[4:5], v[18:19] op_sel_hi:[1,0]
	v_pk_mul_f32 v[2:3], v[2:3], v[18:19] op_sel_hi:[1,0]
	v_pk_mul_f32 v[168:169], v[14:15], v[176:177] op_sel_hi:[1,0]
	v_pk_mul_f32 v[170:171], v[10:11], v[176:177] op_sel_hi:[1,0]
	v_pk_mul_f32 v[172:173], v[16:17], v[176:177] op_sel_hi:[1,0]
	v_pk_mul_f32 v[174:175], v[12:13], v[176:177] op_sel_hi:[1,0]
	v_exp_f32_e32 v168, v168
	v_exp_f32_e32 v169, v169
	v_exp_f32_e32 v170, v170
	v_exp_f32_e32 v171, v171
	v_exp_f32_e32 v172, v172
	v_exp_f32_e32 v173, v173
	v_exp_f32_e32 v174, v174
	v_exp_f32_e32 v175, v175
	v_pk_add_f32 v[168:169], v[168:169], 1.0 op_sel_hi:[1,0]
	v_pk_add_f32 v[170:171], v[170:171], 1.0 op_sel_hi:[1,0]
	v_pk_add_f32 v[172:173], v[172:173], 1.0 op_sel_hi:[1,0]
	v_pk_add_f32 v[174:175], v[174:175], 1.0 op_sel_hi:[1,0]
	v_rcp_f32_e32 v168, v168
	v_rcp_f32_e32 v169, v169
	v_rcp_f32_e32 v170, v170
	v_rcp_f32_e32 v171, v171
	v_rcp_f32_e32 v172, v172
	v_rcp_f32_e32 v173, v173
	v_rcp_f32_e32 v174, v174
	v_rcp_f32_e32 v175, v175
	v_pk_mul_f32 v[168:169], v[14:15], v[168:169]
	v_pk_mul_f32 v[170:171], v[10:11], v[170:171]
	v_pk_mul_f32 v[172:173], v[16:17], v[172:173]
	v_pk_mul_f32 v[174:175], v[12:13], v[174:175]
	v_pk_mul_f32 v[14:15], v[6:7], v[168:169]
	v_pk_mul_f32 v[10:11], v[2:3], v[170:171]
	v_pk_mul_f32 v[16:17], v[8:9], v[172:173]
	v_pk_mul_f32 v[12:13], v[4:5], v[174:175]
	v_cvt_pk_bf16_f32 v2, v14, v15
	v_cvt_pk_bf16_f32 v3, v16, v17
	v_cvt_pk_bf16_f32 v4, v10, v11
	s_sub_i32 s96, s62, s50
	s_mul_i32 s96, s96, 0x1600
	s_ashr_i32 s97, s96, 31
	v_lshl_add_u64 v[6:7], v[246:247], 0, s[96:97]
	s_mov_b64 s[4:5], s[12:13]
	s_mov_b64 s[0:1], s[10:11]
	v_cvt_pk_bf16_f32 v5, v12, v13
	global_store_dwordx4 v[6:7], v[2:5], off nt
	s_cbranch_vccnz .LBB0_669
